# v54: v53 + one V-fragment address computation per tile (shared by the prefetch and the PV reads)
# baseline (speedup 1.0000x reference)
; #define ATT_PV_PRE(VBUF) do { const char* Vc = Vb0 + (VBUF) * 20480 + vlane; \
;         _Pragma("unroll") for (int t = 0; t < 1; ++t) { vlo[t] = ATT_VLO(Vc, t); vhi[t] = ATT_VHI(Vc, t); } } while (0)
; template <int PM> DI void attn_phase(const Params& p, int l, char* smem, int* s_item, int wv, int cidx) {
;     ...
;       const int vlane = (4 * h + ((lane & 15) >> 2)) * 320 + (16 * ((lane >> 4) & 1) + 4 * (lane & 3)) * 2;
;     ...
;         if (active && !shift) ATT_PV_PRE(vcur);
.LBB0_440:
	v_add_u32_e32 v14, s95, v242
	ds_read_b64_tr_b16 v[144:145], v14 offset:34816
	ds_read_b64_tr_b16 v[146:147], v14 offset:37376

; DI unsigned pack2(float a, float b) { f2_t v = {a, b}; bf2_t r = __builtin_convertvector(v, bf2_t); return __builtin_bit_cast(unsigned, r); }
; DI float fexp2(float x) { return __builtin_amdgcn_exp2f(x); }
; template <int PM> DI void attn_phase(const Params& p, int l, char* smem, int* s_item, int wv, int cidx) {
;     ...
;           float ps = 0.f;
; #pragma unroll
;           for (int kb = 0; kb < 2; ++kb)
; #pragma unroll
;             for (int e = 0; e < 16; ++e) { const float pv = fexp2(sacc[kb][e] - m); sacc[kb][e] = pv; ps += pv; }
;           lsum += ps;
; #pragma unroll
;           for (int kb = 0; kb < 2; ++kb)
; #pragma unroll
;             for (int s2 = 0; s2 < 2; ++s2) {
;               u32x4 t;
;               t[0] = pack2(sacc[kb][8 * s2 + 0], sacc[kb][8 * s2 + 1]);
;               t[1] = pack2(sacc[kb][8 * s2 + 2], sacc[kb][8 * s2 + 3]);
;               t[2] = pack2(sacc[kb][8 * s2 + 4], sacc[kb][8 * s2 + 5]);
;               t[3] = pack2(sacc[kb][8 * s2 + 6], sacc[kb][8 * s2 + 7]);
;               pf[kb][s2] = __builtin_bit_cast(bf16x8, t);
;             }
;           if (!shift) ATT_PV_RUN(vcur); else pend = true;
.LBB0_514:
	v_sub_f32_e32 v2, v17, v233
	v_exp_f32_e32 v17, v2
	v_sub_f32_e32 v2, v18, v233
	v_exp_f32_e32 v18, v2
	v_sub_f32_e32 v2, v19, v233
	v_exp_f32_e32 v19, v2
	v_sub_f32_e32 v2, v20, v233
	v_sub_f32_e32 v0, v16, v233
	v_exp_f32_e32 v20, v2
	v_sub_f32_e32 v2, v21, v233
	v_exp_f32_e32 v16, v0
	v_exp_f32_e32 v21, v2
	v_sub_f32_e32 v2, v22, v233
	v_exp_f32_e32 v22, v2
	v_sub_f32_e32 v2, v23, v233
	v_exp_f32_e32 v23, v2
	v_sub_f32_e32 v2, v24, v233
	v_exp_f32_e32 v24, v2
	v_sub_f32_e32 v2, v25, v233
	v_add_f32_e32 v0, 0, v16
	v_exp_f32_e32 v25, v2
	v_sub_f32_e32 v2, v26, v233
	v_add_f32_e32 v0, v17, v0
	v_exp_f32_e32 v26, v2
	v_sub_f32_e32 v2, v27, v233
	v_add_f32_e32 v0, v18, v0
	v_exp_f32_e32 v27, v2
	v_sub_f32_e32 v2, v28, v233
	v_add_f32_e32 v0, v19, v0
	v_exp_f32_e32 v28, v2
	v_sub_f32_e32 v2, v29, v233
	v_add_f32_e32 v0, v20, v0
	v_exp_f32_e32 v29, v2
	v_sub_f32_e32 v2, v30, v233
	v_add_f32_e32 v0, v21, v0
	v_exp_f32_e32 v30, v2
	v_sub_f32_e32 v2, v31, v233
	v_add_f32_e32 v0, v22, v0
	v_exp_f32_e32 v31, v2
	v_sub_f32_e32 v2, v32, v233
	v_add_f32_e32 v0, v23, v0
	v_exp_f32_e32 v32, v2
	v_sub_f32_e32 v2, v33, v233
	v_add_f32_e32 v0, v24, v0
	v_exp_f32_e32 v33, v2
	v_sub_f32_e32 v2, v34, v233
	v_add_f32_e32 v0, v25, v0
	v_exp_f32_e32 v34, v2
	v_sub_f32_e32 v2, v35, v233
	v_add_f32_e32 v0, v26, v0
	v_exp_f32_e32 v35, v2
	v_sub_f32_e32 v2, v36, v233
	v_add_f32_e32 v0, v27, v0
	v_exp_f32_e32 v36, v2
	v_sub_f32_e32 v2, v37, v233
	v_add_f32_e32 v0, v28, v0
	v_exp_f32_e32 v37, v2
	v_sub_f32_e32 v2, v38, v233
	v_add_f32_e32 v0, v29, v0
	v_exp_f32_e32 v38, v2
	v_sub_f32_e32 v2, v39, v233
	v_add_f32_e32 v0, v30, v0
	v_exp_f32_e32 v39, v2
	v_sub_f32_e32 v2, v40, v233
	v_add_f32_e32 v0, v31, v0
	v_exp_f32_e32 v40, v2
	v_sub_f32_e32 v2, v41, v233
	v_add_f32_e32 v0, v32, v0
	v_exp_f32_e32 v41, v2
	v_sub_f32_e32 v2, v42, v233
	v_add_f32_e32 v0, v33, v0
	v_exp_f32_e32 v42, v2
	v_sub_f32_e32 v2, v43, v233
	v_add_f32_e32 v0, v34, v0
	v_exp_f32_e32 v43, v2
	v_sub_f32_e32 v2, v44, v233
	v_add_f32_e32 v0, v35, v0
	v_exp_f32_e32 v44, v2
	v_sub_f32_e32 v2, v45, v233
	v_add_f32_e32 v0, v36, v0
	v_exp_f32_e32 v45, v2
	v_sub_f32_e32 v2, v46, v233
	v_add_f32_e32 v0, v37, v0
	v_exp_f32_e32 v46, v2
	v_sub_f32_e32 v2, v47, v233
	v_add_f32_e32 v0, v38, v0
	v_exp_f32_e32 v47, v2
	v_cvt_pk_bf16_f32 v2, v16, v17
	v_cvt_pk_bf16_f32 v3, v18, v19
	v_cvt_pk_bf16_f32 v4, v20, v21
	v_cvt_pk_bf16_f32 v5, v22, v23
	ds_read_b64_tr_b16 v[52:53], v14 offset:39936
	ds_read_b64_tr_b16 v[54:55], v14 offset:42496
	ds_read_b64_tr_b16 v[56:57], v14 offset:45056
	ds_read_b64_tr_b16 v[58:59], v14 offset:47616
	ds_read_b64_tr_b16 v[60:61], v14 offset:50176
	ds_read_b64_tr_b16 v[62:63], v14 offset:52736
	v_add_f32_e32 v0, v39, v0
	s_waitcnt lgkmcnt(6)
	v_mfma_f32_32x32x16_bf16 v[128:143], v[144:147], v[2:5], v[128:143]
	v_add_f32_e32 v0, v40, v0
	v_add_f32_e32 v0, v41, v0
	v_add_f32_e32 v0, v42, v0
	ds_read_b64_tr_b16 v[64:65], v14 offset:34880
	ds_read_b64_tr_b16 v[66:67], v14 offset:37440
	v_add_f32_e32 v0, v43, v0
	v_add_f32_e32 v0, v44, v0
	v_add_f32_e32 v0, v45, v0
	v_add_f32_e32 v0, v46, v0
	v_add_f32_e32 v0, v47, v0
	v_cvt_pk_bf16_f32 v6, v24, v25
	v_cvt_pk_bf16_f32 v7, v26, v27
	v_cvt_pk_bf16_f32 v8, v28, v29
	v_cvt_pk_bf16_f32 v9, v30, v31
	v_cvt_pk_bf16_f32 v10, v32, v33
	v_cvt_pk_bf16_f32 v11, v34, v35
	v_cvt_pk_bf16_f32 v12, v36, v37
	v_cvt_pk_bf16_f32 v13, v38, v39
	v_cvt_pk_bf16_f32 v48, v40, v41
	v_cvt_pk_bf16_f32 v49, v42, v43
	v_cvt_pk_bf16_f32 v50, v44, v45
	v_cvt_pk_bf16_f32 v51, v46, v47
	s_waitcnt lgkmcnt(6)
	v_mfma_f32_32x32x16_bf16 v[128:143], v[52:55], v[6:9], v[128:143]
	ds_read_b64_tr_b16 v[52:53], v14 offset:40000
	ds_read_b64_tr_b16 v[54:55], v14 offset:42560
	s_waitcnt lgkmcnt(6)
	v_mfma_f32_32x32x16_bf16 v[128:143], v[56:59], v[10:13], v[128:143]
	ds_read_b64_tr_b16 v[56:57], v14 offset:45120
	ds_read_b64_tr_b16 v[58:59], v14 offset:47680
	s_waitcnt lgkmcnt(6)
	v_mfma_f32_32x32x16_bf16 v[128:143], v[60:63], v[48:51], v[128:143]
	ds_read_b64_tr_b16 v[60:61], v14 offset:50240
	ds_read_b64_tr_b16 v[62:63], v14 offset:52800
	s_waitcnt lgkmcnt(6)
	v_mfma_f32_32x32x16_bf16 v[112:127], v[64:67], v[2:5], v[112:127]
	ds_read_b64_tr_b16 v[64:65], v14 offset:34944
	ds_read_b64_tr_b16 v[66:67], v14 offset:37504
	s_waitcnt lgkmcnt(6)
	v_mfma_f32_32x32x16_bf16 v[112:127], v[52:55], v[6:9], v[112:127]
	ds_read_b64_tr_b16 v[52:53], v14 offset:40064
	ds_read_b64_tr_b16 v[54:55], v14 offset:42624
	s_waitcnt lgkmcnt(6)
	v_mfma_f32_32x32x16_bf16 v[112:127], v[56:59], v[10:13], v[112:127]
	ds_read_b64_tr_b16 v[56:57], v14 offset:45184
	ds_read_b64_tr_b16 v[58:59], v14 offset:47744
	s_waitcnt lgkmcnt(6)
	v_mfma_f32_32x32x16_bf16 v[112:127], v[60:63], v[48:51], v[112:127]
	ds_read_b64_tr_b16 v[60:61], v14 offset:50304
	ds_read_b64_tr_b16 v[62:63], v14 offset:52864
	s_waitcnt lgkmcnt(6)
	v_mfma_f32_32x32x16_bf16 v[96:111], v[64:67], v[2:5], v[96:111]
	ds_read_b64_tr_b16 v[144:145], v14 offset:35008
	ds_read_b64_tr_b16 v[146:147], v14 offset:37568
	s_waitcnt lgkmcnt(6)
	v_mfma_f32_32x32x16_bf16 v[96:111], v[52:55], v[6:9], v[96:111]
	ds_read_b64_tr_b16 v[52:53], v14 offset:40128
	ds_read_b64_tr_b16 v[54:55], v14 offset:42688
	s_waitcnt lgkmcnt(6)
	v_mfma_f32_32x32x16_bf16 v[96:111], v[56:59], v[10:13], v[96:111]
	ds_read_b64_tr_b16 v[56:57], v14 offset:45248
	ds_read_b64_tr_b16 v[58:59], v14 offset:47808
	s_waitcnt lgkmcnt(6)
	v_mfma_f32_32x32x16_bf16 v[96:111], v[60:63], v[48:51], v[96:111]
	ds_read_b64_tr_b16 v[60:61], v14 offset:50368
	ds_read_b64_tr_b16 v[62:63], v14 offset:52928
	s_waitcnt lgkmcnt(6)
	v_mfma_f32_32x32x16_bf16 v[80:95], v[144:147], v[2:5], v[80:95]
	s_waitcnt lgkmcnt(4)
	v_mfma_f32_32x32x16_bf16 v[80:95], v[52:55], v[6:9], v[80:95]
	s_waitcnt lgkmcnt(2)
	v_mfma_f32_32x32x16_bf16 v[80:95], v[56:59], v[10:13], v[80:95]
	s_waitcnt lgkmcnt(0)
	v_mfma_f32_32x32x16_bf16 v[80:95], v[60:63], v[48:51], v[80:95]
	v_add_f32_e32 v235, v235, v0
